# P12 split-K hand-off: one L2 write-back + one flag per writer workgroup (after the GEMM's closing barriers) instead of per wave
# speedup vs baseline: 1.0233x; 1.0036x over previous
; #define PG8_STAGE(bufoff, gbase, voff) do { _Pragma("unroll") for (int _i = 0; _i < 2; ++_i) \
;         __builtin_amdgcn_global_load_lds((const unsigned*)((const char*)(gbase) + (voff)[_i]), (PG8_LAS unsigned*)(lds + (bufoff) + ldsw + _i * 8192), 16, 0, 0); } while (0)
; #define PG8_LDA(dst, b, h) do { _Pragma("unroll") for (int m = 0; m < 4; ++m) _Pragma("unroll") for (int k = 0; k < 2; ++k) dst[m][k] = *(const PG8_LAS bf16x8*)(lds + PG8_SA(b, h) + aoff + m * 2048 + k * 1024); } while (0)
; #define PG8_LDB(dst, b, h) do { _Pragma("unroll") for (int n = 0; n < 2; ++n) _Pragma("unroll") for (int k = 0; k < 2; ++k) dst[n][k] = *(const PG8_LAS bf16x8*)(lds + PG8_SB(b, h) + boff + n * 2048 + k * 1024); } while (0)
; #define PG8_MMA(ai, bj, At, Bt) do { __builtin_amdgcn_s_setprio(1); _Pragma("unroll") for (int m = 0; m < 4; ++m) _Pragma("unroll") for (int n = 0; n < 2; ++n) _Pragma("unroll") for (int k = 0; k < 2; ++k) \
;         acc[ai][bj][m][n] = __builtin_amdgcn_mfma_f32_16x16x32_bf16(Bt[n][k], At[m][k], acc[ai][bj][m][n], 0, 0, 0); __builtin_amdgcn_s_setprio(0); } while (0)
; #define PG8_WAIT_V(n) asm volatile("s_waitcnt vmcnt(" #n ")" ::: "memory")
; #define PG8_WAIT_L(n) asm volatile("s_waitcnt lgkmcnt(" #n ")" ::: "memory")
; template <class Epi, class Sched, bool ALIGN_EPI = false, bool SP2 = false>
; __device__ __forceinline__ void gemm_phase(PG8_LAS unsigned char* lds, const Gemm g, const Sched& S, const Epi& E) {
;     ...
;             const bool last = (t == nt - 2);
;             const char* a1 = cA + (size_t)(t + 1) * kstep;
;             const char* a2 = last ? nA : cA + (size_t)(t + 2) * kstep; const char* b2 = last ? nB : cB + (size_t)(t + 2) * kstep;
;             const char* a3 = a2 + kstep; const char* b3 = b2 + kstep;
;             if (last && has_next) S.a_ready(nxt);
;             if constexpr (SP2) {
;             PG8_LDB(B0, 0, 0); PG8_LDB(B1, 0, 1); PG8_SCHED; PG8_LDA(At, 0, 0); PG8_STAGE(PG8_SA(1, 1), a1 + hstep, voffA);
;             PG8_WAIT_V(8); PG8_WAIT_L(0); PG8_BAR; PG8_MMA(0, 0, At, B0); PG8_MMA(0, 1, At, B1); PG8_BAR; PG8_SCHED;
;             PG8_LDA(At, 0, 1); PG8_STAGE(PG8_SB(0, 0), b2, voffB); PG8_STAGE(PG8_SB(0, 1), b2 + hstep, voffB); PG8_STAGE(PG8_SA(0, 0), a2, voffA);
;             PG8_WAIT_V(8); PG8_WAIT_L(0); PG8_BAR; PG8_MMA(1, 0, At, B0); PG8_MMA(1, 1, At, B1); PG8_BAR; PG8_SCHED;
.LBB0_1440:
	ds_read_b128 v[136:139], v143
	ds_read_b128 v[148:151], v143 offset:1024
	ds_read_b128 v[152:155], v143 offset:2048
	ds_read_b128 v[156:159], v143 offset:3072
	ds_read_b128 v[160:163], v144
	ds_read_b128 v[164:167], v144 offset:1024
	ds_read_b128 v[168:171], v144 offset:2048
	ds_read_b128 v[172:175], v144 offset:3072
	s_add_u32 s3, s22, 0xfff50080
	s_addc_u32 s24, s23, -1
	s_cmp_eq_u32 s51, 18
	s_cselect_b32 s27, s21, s24
	s_cselect_b32 s26, s20, s3
	s_cselect_b32 s25, s5, s50
	s_cselect_b32 s24, s4, s49
	v_lshl_add_u64 v[212:213], s[22:23], 0, v[132:133]
	s_add_i32 m0, s37, 0xc000
	ds_read_b128 v[180:183], v145
	ds_read_b128 v[184:187], v145 offset:1024
	ds_read_b128 v[188:191], v145 offset:2048
	ds_read_b128 v[192:195], v145 offset:3072
	ds_read_b128 v[196:199], v145 offset:4096
	ds_read_b128 v[200:203], v145 offset:5120
	ds_read_b128 v[204:207], v145 offset:6144
	ds_read_b128 v[208:211], v145 offset:7168
	global_load_lds_dwordx4 v[212:213], off
	v_lshl_add_u64 v[212:213], s[22:23], 0, v[134:135]
	s_add_i32 m0, s37, 0xe000
	s_nop 0
	global_load_lds_dwordx4 v[212:213], off
	s_waitcnt vmcnt(8)
	s_waitcnt lgkmcnt(0)
	s_barrier
	s_setprio 1
	s_waitcnt lgkmcnt(0)
	v_mfma_f32_16x16x32_bf16 v[124:127], v[136:139], v[180:183], v[124:127]
	v_mfma_f32_16x16x32_bf16 v[120:123], v[152:155], v[180:183], v[120:123]
	v_mfma_f32_16x16x32_bf16 v[112:115], v[136:139], v[188:191], v[112:115]
	v_mfma_f32_16x16x32_bf16 v[104:107], v[152:155], v[188:191], v[104:107]
	v_mfma_f32_16x16x32_bf16 v[96:99], v[136:139], v[196:199], v[96:99]
	v_mfma_f32_16x16x32_bf16 v[88:91], v[152:155], v[196:199], v[88:91]
	v_mfma_f32_16x16x32_bf16 v[80:83], v[136:139], v[204:207], v[80:83]
	v_mfma_f32_16x16x32_bf16 v[72:75], v[152:155], v[204:207], v[72:75]
	v_mfma_f32_16x16x32_bf16 v[124:127], v[148:151], v[184:187], v[124:127]
	v_mfma_f32_16x16x32_bf16 v[120:123], v[156:159], v[184:187], v[120:123]
	v_mfma_f32_16x16x32_bf16 v[112:115], v[148:151], v[192:195], v[112:115]
	v_mfma_f32_16x16x32_bf16 v[104:107], v[156:159], v[192:195], v[104:107]
	v_mfma_f32_16x16x32_bf16 v[96:99], v[148:151], v[200:203], v[96:99]
	v_mfma_f32_16x16x32_bf16 v[88:91], v[156:159], v[200:203], v[88:91]
	v_mfma_f32_16x16x32_bf16 v[80:83], v[148:151], v[208:211], v[80:83]
	v_mfma_f32_16x16x32_bf16 v[72:75], v[156:159], v[208:211], v[72:75]
	s_setprio 0
	s_setprio 1
	v_mfma_f32_16x16x32_bf16 v[116:119], v[160:163], v[180:183], v[116:119]
	v_mfma_f32_16x16x32_bf16 v[108:111], v[168:171], v[180:183], v[108:111]
	v_mfma_f32_16x16x32_bf16 v[100:103], v[160:163], v[188:191], v[100:103]
	v_mfma_f32_16x16x32_bf16 v[92:95], v[168:171], v[188:191], v[92:95]
	v_mfma_f32_16x16x32_bf16 v[84:87], v[160:163], v[196:199], v[84:87]
	v_mfma_f32_16x16x32_bf16 v[76:79], v[168:171], v[196:199], v[76:79]
	v_mfma_f32_16x16x32_bf16 v[68:71], v[160:163], v[204:207], v[68:71]
	v_mfma_f32_16x16x32_bf16 v[64:67], v[168:171], v[204:207], v[64:67]
	v_mfma_f32_16x16x32_bf16 v[116:119], v[164:167], v[184:187], v[116:119]
	v_mfma_f32_16x16x32_bf16 v[108:111], v[172:175], v[184:187], v[108:111]
	v_mfma_f32_16x16x32_bf16 v[100:103], v[164:167], v[192:195], v[100:103]
	v_mfma_f32_16x16x32_bf16 v[92:95], v[172:175], v[192:195], v[92:95]
	v_mfma_f32_16x16x32_bf16 v[84:87], v[164:167], v[200:203], v[84:87]
	v_mfma_f32_16x16x32_bf16 v[76:79], v[172:175], v[200:203], v[76:79]
	v_mfma_f32_16x16x32_bf16 v[68:71], v[164:167], v[208:211], v[68:71]
	v_mfma_f32_16x16x32_bf16 v[64:67], v[172:175], v[208:211], v[64:67]
	s_setprio 0
	s_barrier
	s_add_i32 s3, s43, s36
	v_lshl_add_u64 v[212:213], s[24:25], 0, v[128:129]
	s_mov_b32 m0, s3
	ds_read_b128 v[180:183], v145 offset:16384
	ds_read_b128 v[184:187], v145 offset:17408
	ds_read_b128 v[188:191], v145 offset:18432
	ds_read_b128 v[192:195], v145 offset:19456
	ds_read_b128 v[196:199], v145 offset:20480
	ds_read_b128 v[200:203], v145 offset:21504
	ds_read_b128 v[204:207], v145 offset:22528
	ds_read_b128 v[208:211], v145 offset:23552
	global_load_lds_dwordx4 v[212:213], off
	s_add_i32 m0, s3, 0x2000
	s_add_u32 s60, s24, 0xb0000
	v_lshl_add_u64 v[214:215], s[24:25], 0, v[130:131]
	s_addc_u32 s61, s25, 0
	s_add_i32 s3, s44, s36
	global_load_lds_dwordx4 v[214:215], off
	v_lshl_add_u64 v[216:217], s[60:61], 0, v[128:129]
	s_mov_b32 m0, s3
	v_lshl_add_u64 v[218:219], s[26:27], 0, v[130:131]
	global_load_lds_dwordx4 v[216:217], off
	v_lshl_add_u64 v[216:217], s[60:61], 0, v[130:131]
	s_add_i32 m0, s3, 0x2000
	s_nop 0
	global_load_lds_dwordx4 v[216:217], off
	v_lshl_add_u64 v[216:217], s[26:27], 0, v[128:129]
	s_mov_b32 m0, s37
	s_nop 0
	global_load_lds_dwordx4 v[216:217], off
	s_mov_b32 m0, s38
	s_nop 0
	global_load_lds_dwordx4 v[218:219], off
	s_waitcnt vmcnt(8)
	s_waitcnt lgkmcnt(0)
	s_barrier
; #define PG8_STAGE(bufoff, gbase, voff) do { _Pragma("unroll") for (int _i = 0; _i < 2; ++_i) \
;         __builtin_amdgcn_global_load_lds((const unsigned*)((const char*)(gbase) + (voff)[_i]), (PG8_LAS unsigned*)(lds + (bufoff) + ldsw + _i * 8192), 16, 0, 0); } while (0)
; #define PG8_LDA(dst, b, h) do { _Pragma("unroll") for (int m = 0; m < 4; ++m) _Pragma("unroll") for (int k = 0; k < 2; ++k) dst[m][k] = *(const PG8_LAS bf16x8*)(lds + PG8_SA(b, h) + aoff + m * 2048 + k * 1024); } while (0)
; #define PG8_LDB(dst, b, h) do { _Pragma("unroll") for (int n = 0; n < 2; ++n) _Pragma("unroll") for (int k = 0; k < 2; ++k) dst[n][k] = *(const PG8_LAS bf16x8*)(lds + PG8_SB(b, h) + boff + n * 2048 + k * 1024); } while (0)
; #define PG8_MMA(ai, bj, At, Bt) do { __builtin_amdgcn_s_setprio(1); _Pragma("unroll") for (int m = 0; m < 4; ++m) _Pragma("unroll") for (int n = 0; n < 2; ++n) _Pragma("unroll") for (int k = 0; k < 2; ++k) \
;         acc[ai][bj][m][n] = __builtin_amdgcn_mfma_f32_16x16x32_bf16(Bt[n][k], At[m][k], acc[ai][bj][m][n], 0, 0, 0); __builtin_amdgcn_s_setprio(0); } while (0)
; #define PG8_WAIT_V(n) asm volatile("s_waitcnt vmcnt(" #n ")" ::: "memory")
; #define PG8_WAIT_L(n) asm volatile("s_waitcnt lgkmcnt(" #n ")" ::: "memory")
; #define PG8_BAR __builtin_amdgcn_s_barrier()
; #define PG8_SCHED __builtin_amdgcn_sched_barrier(0)
; template <class Epi, class Sched, bool ALIGN_EPI = false, bool SP2 = false>
; __device__ __forceinline__ void gemm_phase(PG8_LAS unsigned char* lds, const Gemm g, const Sched& S, const Epi& E) {
;     ...
;             PG8_WAIT_V(8); PG8_WAIT_L(0); PG8_BAR; PG8_MMA(1, 0, At, B0); PG8_MMA(1, 1, At, B1); PG8_BAR; PG8_SCHED;
;             PG8_LDB(B0, 1, 0); PG8_LDB(B1, 1, 1); PG8_SCHED; PG8_LDA(At, 1, 0); PG8_STAGE(PG8_SA(0, 1), a2 + hstep, voffA);
;             PG8_WAIT_V(8); PG8_WAIT_L(0); PG8_BAR; PG8_MMA(0, 0, At, B0); PG8_MMA(0, 1, At, B1); PG8_BAR; PG8_SCHED;
	s_setprio 1
	s_waitcnt lgkmcnt(0)
	v_mfma_f32_16x16x32_bf16 v[60:63], v[136:139], v[180:183], v[60:63]
	v_mfma_f32_16x16x32_bf16 v[56:59], v[152:155], v[180:183], v[56:59]
	v_mfma_f32_16x16x32_bf16 v[48:51], v[136:139], v[188:191], v[48:51]
	v_mfma_f32_16x16x32_bf16 v[40:43], v[152:155], v[188:191], v[40:43]
	v_mfma_f32_16x16x32_bf16 v[32:35], v[136:139], v[196:199], v[32:35]
	v_mfma_f32_16x16x32_bf16 v[24:27], v[152:155], v[196:199], v[24:27]
	v_mfma_f32_16x16x32_bf16 v[16:19], v[136:139], v[204:207], v[16:19]
	v_mfma_f32_16x16x32_bf16 v[8:11], v[152:155], v[204:207], v[8:11]
	v_mfma_f32_16x16x32_bf16 v[60:63], v[148:151], v[184:187], v[60:63]
	v_mfma_f32_16x16x32_bf16 v[56:59], v[156:159], v[184:187], v[56:59]
	v_mfma_f32_16x16x32_bf16 v[48:51], v[148:151], v[192:195], v[48:51]
	v_mfma_f32_16x16x32_bf16 v[40:43], v[156:159], v[192:195], v[40:43]
	v_mfma_f32_16x16x32_bf16 v[32:35], v[148:151], v[200:203], v[32:35]
	v_mfma_f32_16x16x32_bf16 v[24:27], v[156:159], v[200:203], v[24:27]
	v_mfma_f32_16x16x32_bf16 v[16:19], v[148:151], v[208:211], v[16:19]
	v_mfma_f32_16x16x32_bf16 v[8:11], v[156:159], v[208:211], v[8:11]
	s_setprio 0
	s_setprio 1
	v_mfma_f32_16x16x32_bf16 v[52:55], v[160:163], v[180:183], v[52:55]
	v_mfma_f32_16x16x32_bf16 v[44:47], v[168:171], v[180:183], v[44:47]
	v_mfma_f32_16x16x32_bf16 v[36:39], v[160:163], v[188:191], v[36:39]
	v_mfma_f32_16x16x32_bf16 v[28:31], v[168:171], v[188:191], v[28:31]
	v_mfma_f32_16x16x32_bf16 v[20:23], v[160:163], v[196:199], v[20:23]
	v_mfma_f32_16x16x32_bf16 v[12:15], v[168:171], v[196:199], v[12:15]
	v_mfma_f32_16x16x32_bf16 v[4:7], v[160:163], v[204:207], v[4:7]
	v_mfma_f32_16x16x32_bf16 v[0:3], v[168:171], v[204:207], v[0:3]
	v_mfma_f32_16x16x32_bf16 v[52:55], v[164:167], v[184:187], v[52:55]
	v_mfma_f32_16x16x32_bf16 v[44:47], v[172:175], v[184:187], v[44:47]
	v_mfma_f32_16x16x32_bf16 v[36:39], v[164:167], v[192:195], v[36:39]
	v_mfma_f32_16x16x32_bf16 v[28:31], v[172:175], v[192:195], v[28:31]
	v_mfma_f32_16x16x32_bf16 v[20:23], v[164:167], v[200:203], v[20:23]
	v_mfma_f32_16x16x32_bf16 v[12:15], v[172:175], v[200:203], v[12:15]
	v_mfma_f32_16x16x32_bf16 v[4:7], v[164:167], v[208:211], v[4:7]
	v_mfma_f32_16x16x32_bf16 v[0:3], v[172:175], v[208:211], v[0:3]
	s_setprio 0
	s_barrier
	s_add_i32 s3, 0, 0x18000
	v_add_u32_e32 v147, s3, v141
	s_add_i32 s33, 0, 0x1c000
	ds_read_b128 v[136:139], v147
	ds_read_b128 v[148:151], v147 offset:1024
	ds_read_b128 v[152:155], v147 offset:2048
	ds_read_b128 v[156:159], v147 offset:3072
	v_add_u32_e32 v147, s33, v141
	ds_read_b128 v[160:163], v147
	ds_read_b128 v[164:167], v147 offset:1024
	ds_read_b128 v[168:171], v147 offset:2048
	ds_read_b128 v[172:175], v147 offset:3072
	s_add_u32 s26, s26, 0xb0000
	s_addc_u32 s27, s27, 0
	s_mov_b32 m0, s39
	v_lshl_add_u64 v[220:221], s[26:27], 0, v[128:129]
	ds_read_b128 v[180:183], v145 offset:32768
	ds_read_b128 v[184:187], v145 offset:33792
	ds_read_b128 v[188:191], v145 offset:34816
	ds_read_b128 v[192:195], v145 offset:35840
	ds_read_b128 v[196:199], v145 offset:36864
	ds_read_b128 v[200:203], v145 offset:37888
	ds_read_b128 v[204:207], v145 offset:38912
	ds_read_b128 v[208:211], v145 offset:39936
	global_load_lds_dwordx4 v[220:221], off
	v_lshl_add_u64 v[220:221], s[26:27], 0, v[130:131]
	s_mov_b32 m0, s40
	s_nop 0
	global_load_lds_dwordx4 v[220:221], off
	s_waitcnt vmcnt(8)
	s_waitcnt lgkmcnt(0)
	s_barrier
	s_setprio 1
	s_waitcnt lgkmcnt(0)
	v_mfma_f32_16x16x32_bf16 v[124:127], v[136:139], v[180:183], v[124:127]
	v_mfma_f32_16x16x32_bf16 v[120:123], v[152:155], v[180:183], v[120:123]
	v_mfma_f32_16x16x32_bf16 v[112:115], v[136:139], v[188:191], v[112:115]
	v_mfma_f32_16x16x32_bf16 v[104:107], v[152:155], v[188:191], v[104:107]
	v_mfma_f32_16x16x32_bf16 v[96:99], v[136:139], v[196:199], v[96:99]
	v_mfma_f32_16x16x32_bf16 v[88:91], v[152:155], v[196:199], v[88:91]
	v_mfma_f32_16x16x32_bf16 v[80:83], v[136:139], v[204:207], v[80:83]
	v_mfma_f32_16x16x32_bf16 v[72:75], v[152:155], v[204:207], v[72:75]
	v_mfma_f32_16x16x32_bf16 v[124:127], v[148:151], v[184:187], v[124:127]
	v_mfma_f32_16x16x32_bf16 v[120:123], v[156:159], v[184:187], v[120:123]
	v_mfma_f32_16x16x32_bf16 v[112:115], v[148:151], v[192:195], v[112:115]
	v_mfma_f32_16x16x32_bf16 v[104:107], v[156:159], v[192:195], v[104:107]
	v_mfma_f32_16x16x32_bf16 v[96:99], v[148:151], v[200:203], v[96:99]
	v_mfma_f32_16x16x32_bf16 v[88:91], v[156:159], v[200:203], v[88:91]
	v_mfma_f32_16x16x32_bf16 v[80:83], v[148:151], v[208:211], v[80:83]
	v_mfma_f32_16x16x32_bf16 v[72:75], v[156:159], v[208:211], v[72:75]
	s_setprio 0
	s_setprio 1
	v_mfma_f32_16x16x32_bf16 v[116:119], v[160:163], v[180:183], v[116:119]
	v_mfma_f32_16x16x32_bf16 v[108:111], v[168:171], v[180:183], v[108:111]
	v_mfma_f32_16x16x32_bf16 v[100:103], v[160:163], v[188:191], v[100:103]
	v_mfma_f32_16x16x32_bf16 v[92:95], v[168:171], v[188:191], v[92:95]
	v_mfma_f32_16x16x32_bf16 v[84:87], v[160:163], v[196:199], v[84:87]
	v_mfma_f32_16x16x32_bf16 v[76:79], v[168:171], v[196:199], v[76:79]
	v_mfma_f32_16x16x32_bf16 v[68:71], v[160:163], v[204:207], v[68:71]
	v_mfma_f32_16x16x32_bf16 v[64:67], v[168:171], v[204:207], v[64:67]
	v_mfma_f32_16x16x32_bf16 v[116:119], v[164:167], v[184:187], v[116:119]
	v_mfma_f32_16x16x32_bf16 v[108:111], v[172:175], v[184:187], v[108:111]
	v_mfma_f32_16x16x32_bf16 v[100:103], v[164:167], v[192:195], v[100:103]
	v_mfma_f32_16x16x32_bf16 v[92:95], v[172:175], v[192:195], v[92:95]
	v_mfma_f32_16x16x32_bf16 v[84:87], v[164:167], v[200:203], v[84:87]
	v_mfma_f32_16x16x32_bf16 v[76:79], v[172:175], v[200:203], v[76:79]
	v_mfma_f32_16x16x32_bf16 v[68:71], v[164:167], v[208:211], v[68:71]
	v_mfma_f32_16x16x32_bf16 v[64:67], v[172:175], v[208:211], v[64:67]
	s_setprio 0
	s_barrier
; #define PG8_STAGE(bufoff, gbase, voff) do { _Pragma("unroll") for (int _i = 0; _i < 2; ++_i) \
;         __builtin_amdgcn_global_load_lds((const unsigned*)((const char*)(gbase) + (voff)[_i]), (PG8_LAS unsigned*)(lds + (bufoff) + ldsw + _i * 8192), 16, 0, 0); } while (0)
; #define PG8_LDA(dst, b, h) do { _Pragma("unroll") for (int m = 0; m < 4; ++m) _Pragma("unroll") for (int k = 0; k < 2; ++k) dst[m][k] = *(const PG8_LAS bf16x8*)(lds + PG8_SA(b, h) + aoff + m * 2048 + k * 1024); } while (0)
; #define PG8_MMA(ai, bj, At, Bt) do { __builtin_amdgcn_s_setprio(1); _Pragma("unroll") for (int m = 0; m < 4; ++m) _Pragma("unroll") for (int n = 0; n < 2; ++n) _Pragma("unroll") for (int k = 0; k < 2; ++k) \
;         acc[ai][bj][m][n] = __builtin_amdgcn_mfma_f32_16x16x32_bf16(Bt[n][k], At[m][k], acc[ai][bj][m][n], 0, 0, 0); __builtin_amdgcn_s_setprio(0); } while (0)
; #define PG8_WAIT_V(n) asm volatile("s_waitcnt vmcnt(" #n ")" ::: "memory")
; #define PG8_WAIT_L(n) asm volatile("s_waitcnt lgkmcnt(" #n ")" ::: "memory")
; #define PG8_BAR __builtin_amdgcn_s_barrier()
; #define PG8_SCHED __builtin_amdgcn_sched_barrier(0)
; template <class Epi, class Sched, bool ALIGN_EPI = false, bool SP2 = false>
; __device__ __forceinline__ void gemm_phase(PG8_LAS unsigned char* lds, const Gemm g, const Sched& S, const Epi& E) {
;     ...
;         for (int t = 0; t < nt; t += 2) {
;             const bool last = (t == nt - 2);
;             const char* a1 = cA + (size_t)(t + 1) * kstep;
;             const char* a2 = last ? nA : cA + (size_t)(t + 2) * kstep; const char* b2 = last ? nB : cB + (size_t)(t + 2) * kstep;
;     ...
;             PG8_LDA(At, 1, 1); PG8_STAGE(PG8_SB(1, 0), b3, voffB); PG8_STAGE(PG8_SB(1, 1), b3 + hstep, voffB); PG8_STAGE(PG8_SA(1, 0), a3, voffA);
;             PG8_WAIT_V(8); PG8_WAIT_L(0); PG8_BAR; PG8_MMA(1, 0, At, B0); PG8_MMA(1, 1, At, B1); PG8_BAR; PG8_SCHED;
	s_add_i32 s3, s3, s36
	v_lshl_add_u64 v[212:213], v[212:213], 0, s[16:17]
	s_mov_b32 m0, s3
	ds_read_b128 v[180:183], v145 offset:49152
	ds_read_b128 v[184:187], v145 offset:50176
	ds_read_b128 v[188:191], v145 offset:51200
	ds_read_b128 v[192:195], v145 offset:52224
	ds_read_b128 v[196:199], v145 offset:53248
	ds_read_b128 v[200:203], v145 offset:54272
	ds_read_b128 v[204:207], v145 offset:55296
	ds_read_b128 v[208:211], v145 offset:56320
	global_load_lds_dwordx4 v[212:213], off
	s_add_i32 m0, s3, 0x2000
	s_add_u32 s24, s24, 0xb0080
	v_lshl_add_u64 v[212:213], v[214:215], 0, s[16:17]
	s_addc_u32 s25, s25, 0
	s_add_i32 s3, s33, s36
	global_load_lds_dwordx4 v[212:213], off
	v_lshl_add_u64 v[212:213], s[24:25], 0, v[128:129]
	s_mov_b32 m0, s3
	s_nop 0
	global_load_lds_dwordx4 v[212:213], off
	v_lshl_add_u64 v[212:213], s[24:25], 0, v[130:131]
	s_add_i32 m0, s3, 0x2000
	s_nop 0
	global_load_lds_dwordx4 v[212:213], off
	v_lshl_add_u64 v[212:213], v[216:217], 0, s[16:17]
	s_mov_b32 m0, s41
	s_nop 0
	global_load_lds_dwordx4 v[212:213], off
	v_lshl_add_u64 v[212:213], v[218:219], 0, s[16:17]
	s_mov_b32 m0, s42
	s_nop 0
	global_load_lds_dwordx4 v[212:213], off
	s_waitcnt vmcnt(8)
	s_waitcnt lgkmcnt(0)
	s_barrier
	s_setprio 1
	s_waitcnt lgkmcnt(0)
	v_mfma_f32_16x16x32_bf16 v[60:63], v[136:139], v[180:183], v[60:63]
	v_mfma_f32_16x16x32_bf16 v[56:59], v[152:155], v[180:183], v[56:59]
	v_mfma_f32_16x16x32_bf16 v[48:51], v[136:139], v[188:191], v[48:51]
	v_mfma_f32_16x16x32_bf16 v[40:43], v[152:155], v[188:191], v[40:43]
	v_mfma_f32_16x16x32_bf16 v[32:35], v[136:139], v[196:199], v[32:35]
	v_mfma_f32_16x16x32_bf16 v[24:27], v[152:155], v[196:199], v[24:27]
	v_mfma_f32_16x16x32_bf16 v[16:19], v[136:139], v[204:207], v[16:19]
	v_mfma_f32_16x16x32_bf16 v[8:11], v[152:155], v[204:207], v[8:11]
	v_mfma_f32_16x16x32_bf16 v[60:63], v[148:151], v[184:187], v[60:63]
	v_mfma_f32_16x16x32_bf16 v[56:59], v[156:159], v[184:187], v[56:59]
	v_mfma_f32_16x16x32_bf16 v[48:51], v[148:151], v[192:195], v[48:51]
	v_mfma_f32_16x16x32_bf16 v[40:43], v[156:159], v[192:195], v[40:43]
	v_mfma_f32_16x16x32_bf16 v[32:35], v[148:151], v[200:203], v[32:35]
	v_mfma_f32_16x16x32_bf16 v[24:27], v[156:159], v[200:203], v[24:27]
	v_mfma_f32_16x16x32_bf16 v[16:19], v[148:151], v[208:211], v[16:19]
	v_mfma_f32_16x16x32_bf16 v[8:11], v[156:159], v[208:211], v[8:11]
	s_setprio 0
	s_setprio 1
	v_mfma_f32_16x16x32_bf16 v[52:55], v[160:163], v[180:183], v[52:55]
	v_mfma_f32_16x16x32_bf16 v[44:47], v[168:171], v[180:183], v[44:47]
	v_mfma_f32_16x16x32_bf16 v[36:39], v[160:163], v[188:191], v[36:39]
	v_mfma_f32_16x16x32_bf16 v[28:31], v[168:171], v[188:191], v[28:31]
	v_mfma_f32_16x16x32_bf16 v[20:23], v[160:163], v[196:199], v[20:23]
	v_mfma_f32_16x16x32_bf16 v[12:15], v[168:171], v[196:199], v[12:15]
	v_mfma_f32_16x16x32_bf16 v[4:7], v[160:163], v[204:207], v[4:7]
	v_mfma_f32_16x16x32_bf16 v[0:3], v[168:171], v[204:207], v[0:3]
	v_mfma_f32_16x16x32_bf16 v[52:55], v[164:167], v[184:187], v[52:55]
	v_mfma_f32_16x16x32_bf16 v[44:47], v[172:175], v[184:187], v[44:47]
	v_mfma_f32_16x16x32_bf16 v[36:39], v[164:167], v[192:195], v[36:39]
	v_mfma_f32_16x16x32_bf16 v[28:31], v[172:175], v[192:195], v[28:31]
	v_mfma_f32_16x16x32_bf16 v[20:23], v[164:167], v[200:203], v[20:23]
	v_mfma_f32_16x16x32_bf16 v[12:15], v[172:175], v[200:203], v[12:15]
	v_mfma_f32_16x16x32_bf16 v[4:7], v[164:167], v[208:211], v[4:7]
	v_mfma_f32_16x16x32_bf16 v[0:3], v[172:175], v[208:211], v[0:3]
	s_setprio 0
	s_barrier
	s_add_i32 s51, s51, 2
	s_add_u32 s22, s22, 0x100
	s_addc_u32 s23, s23, 0
	s_add_u32 s49, s49, 0x100
	s_addc_u32 s50, s50, 0
	s_cmp_gt_u32 s51, 19
	s_cbranch_scc0 .LBB0_1440
; template <class Epi, class Sched, bool ALIGN_EPI = false, bool SP2 = false>
; __device__ __forceinline__ void gemm_phase(PG8_LAS unsigned char* lds, const Gemm g, const Sched& S, const Epi& E) {
;     ...
;         if constexpr (!Epi::AFTER_DRAIN) { E(acc, cur, wr, wc, fr, fq); S.done(cur); }
;         if (!has_next) break;
	s_and_b32 s100, s2, 15
	v_readfirstlane_b32 s101, v178
	s_lshl_b32 s98, s100, 18
	s_lshr_b32 s101, s101, 6
	s_lshl_b32 s99, s101, 15
	s_add_u32 s98, s98, s99
	s_lshl_b32 s100, s100, 2
	s_add_u32 s98, s54, s98
	s_addc_u32 s99, s55, 0
	s_add_u32 s98, s98, 0x9a00000
	s_addc_u32 s99, s99, 0
	s_add_u32 s100, s54, s100
	s_addc_u32 s101, s55, 0
	s_add_u32 s100, s100, 0x22a2000
	s_addc_u32 s101, s101, 0
	v_lshlrev_b32_e32 v160, 4, v176
	v_mov_b32_e32 v161, 0
	s_cmp_lt_u32 s2, 16
	s_cbranch_scc1 .Lsk_reader
	global_store_dwordx4 v160, v[0:3], s[98:99]
	s_add_u32 s98, s98, 0x400
	s_addc_u32 s99, s99, 0
	global_store_dwordx4 v160, v[4:7], s[98:99]
	s_add_u32 s98, s98, 0x400
	s_addc_u32 s99, s99, 0
	global_store_dwordx4 v160, v[8:11], s[98:99]
	s_add_u32 s98, s98, 0x400
	s_addc_u32 s99, s99, 0
	global_store_dwordx4 v160, v[12:15], s[98:99]
	s_add_u32 s98, s98, 0x400
	s_addc_u32 s99, s99, 0
	global_store_dwordx4 v160, v[16:19], s[98:99]
	s_add_u32 s98, s98, 0x400
	s_addc_u32 s99, s99, 0
	global_store_dwordx4 v160, v[20:23], s[98:99]
	s_add_u32 s98, s98, 0x400
	s_addc_u32 s99, s99, 0
	global_store_dwordx4 v160, v[24:27], s[98:99]
	s_add_u32 s98, s98, 0x400
	s_addc_u32 s99, s99, 0
	global_store_dwordx4 v160, v[28:31], s[98:99]
	s_add_u32 s98, s98, 0x400
	s_addc_u32 s99, s99, 0
	global_store_dwordx4 v160, v[32:35], s[98:99]
	s_add_u32 s98, s98, 0x400
	s_addc_u32 s99, s99, 0
	global_store_dwordx4 v160, v[36:39], s[98:99]
	s_add_u32 s98, s98, 0x400
	s_addc_u32 s99, s99, 0
	global_store_dwordx4 v160, v[40:43], s[98:99]
	s_add_u32 s98, s98, 0x400
	s_addc_u32 s99, s99, 0
	global_store_dwordx4 v160, v[44:47], s[98:99]
	s_add_u32 s98, s98, 0x400
	s_addc_u32 s99, s99, 0
	global_store_dwordx4 v160, v[48:51], s[98:99]
	s_add_u32 s98, s98, 0x400
	s_addc_u32 s99, s99, 0
	global_store_dwordx4 v160, v[52:55], s[98:99]
	s_add_u32 s98, s98, 0x400
	s_addc_u32 s99, s99, 0
	global_store_dwordx4 v160, v[56:59], s[98:99]
	s_add_u32 s98, s98, 0x400
	s_addc_u32 s99, s99, 0
	global_store_dwordx4 v160, v[60:63], s[98:99]
	s_add_u32 s98, s98, 0x400
	s_addc_u32 s99, s99, 0
	global_store_dwordx4 v160, v[64:67], s[98:99]
	s_add_u32 s98, s98, 0x400
	s_addc_u32 s99, s99, 0
	global_store_dwordx4 v160, v[68:71], s[98:99]
	s_add_u32 s98, s98, 0x400
	s_addc_u32 s99, s99, 0
	global_store_dwordx4 v160, v[72:75], s[98:99]
	s_add_u32 s98, s98, 0x400
	s_addc_u32 s99, s99, 0
	global_store_dwordx4 v160, v[76:79], s[98:99]
	s_add_u32 s98, s98, 0x400
	s_addc_u32 s99, s99, 0
	global_store_dwordx4 v160, v[80:83], s[98:99]
	s_add_u32 s98, s98, 0x400
	s_addc_u32 s99, s99, 0
	global_store_dwordx4 v160, v[84:87], s[98:99]
	s_add_u32 s98, s98, 0x400
	s_addc_u32 s99, s99, 0
	global_store_dwordx4 v160, v[88:91], s[98:99]
	s_add_u32 s98, s98, 0x400
	s_addc_u32 s99, s99, 0
	global_store_dwordx4 v160, v[92:95], s[98:99]
	s_add_u32 s98, s98, 0x400
	s_addc_u32 s99, s99, 0
	global_store_dwordx4 v160, v[96:99], s[98:99]
	s_add_u32 s98, s98, 0x400
	s_addc_u32 s99, s99, 0
	global_store_dwordx4 v160, v[100:103], s[98:99]
	s_add_u32 s98, s98, 0x400
	s_addc_u32 s99, s99, 0
	global_store_dwordx4 v160, v[104:107], s[98:99]
	s_add_u32 s98, s98, 0x400
	s_addc_u32 s99, s99, 0
	global_store_dwordx4 v160, v[108:111], s[98:99]
	s_add_u32 s98, s98, 0x400
	s_addc_u32 s99, s99, 0
	global_store_dwordx4 v160, v[112:115], s[98:99]
	s_add_u32 s98, s98, 0x400
	s_addc_u32 s99, s99, 0
	global_store_dwordx4 v160, v[116:119], s[98:99]
	s_add_u32 s98, s98, 0x400
	s_addc_u32 s99, s99, 0
	global_store_dwordx4 v160, v[120:123], s[98:99]
	s_add_u32 s98, s98, 0x400
	s_addc_u32 s99, s99, 0
	global_store_dwordx4 v160, v[124:127], s[98:99]
	s_add_u32 s98, s98, 0x400
	s_addc_u32 s99, s99, 0
	s_branch .LBB0_1428

; #define PG8_WAIT_V(n) asm volatile("s_waitcnt vmcnt(" #n ")" ::: "memory")
; #define PG8_BAR __builtin_amdgcn_s_barrier()
; template <class Epi, class Sched, bool ALIGN_EPI = false, bool SP2 = false>
; __device__ __forceinline__ void gemm_phase(PG8_LAS unsigned char* lds, const Gemm g, const Sched& S, const Epi& E) {
;     ...
;     PG8_WAIT_V(0);
;     if constexpr (!ALIGN_EPI) { if (wr == 0) PG8_BAR; }
;     PG8_BAR;
.LBB0_1459:
	s_barrier
	s_cmp_lt_u32 s2, 16
	s_cbranch_scc1 .Lsk_nowb
	v_cmp_eq_u32_e32 vcc, 0, v178
	s_and_saveexec_b64 s[0:1], vcc
	s_cbranch_execz .Lsk_wbj
	buffer_wbl2 sc1
	s_waitcnt vmcnt(0)
	s_and_b32 s100, s2, 15
	s_lshl_b32 s100, s100, 2
	s_add_u32 s100, s54, s100
	s_addc_u32 s101, s55, 0
	s_add_u32 s100, s100, 0x22a2000
	s_addc_u32 s101, s101, 0
	v_mov_b32_e32 v161, 0
	v_mov_b32_e32 v162, 1
	global_atomic_add v161, v162, s[100:101]

; __device__ __forceinline__ unsigned xb_ld(unsigned* p)              { return __hip_atomic_load(p, __ATOMIC_RELAXED, __HIP_MEMORY_SCOPE_AGENT); }
; __device__ __forceinline__ unsigned xb_add(unsigned* p, unsigned v) { return __hip_atomic_fetch_add(p, v, __ATOMIC_RELAXED, __HIP_MEMORY_SCOPE_AGENT); }
; #define XB_SPIN(cond, bar) do { unsigned _sp = 0; while (cond) { __builtin_amdgcn_s_sleep(1); \
;     if ((++_sp & 255u) == 0u) { if (xb_ld(&(bar)[XB_TMO])) break; if (_sp > XB_SPIN_CAP) { atomicAdd(&(bar)[XB_TMO], 1u); break; } } } } while (0)
; __device__ __forceinline__ void xcd_barrier(const XcdBarrier& b) {
;     asm volatile("s_waitcnt vmcnt(0)" ::: "memory");
;     __syncthreads();
;     if (threadIdx.x == 0) {
;         unsigned* bar = b.bar;
;         __builtin_amdgcn_s_waitcnt(0);
;         unsigned nloc = b.st[0], nx = b.st[1];
;         if (nloc == 0u) { xcd_barrier_complete(bar, b.x, nloc, nx); b.st[0] = nloc; b.st[1] = nx; }
;         const unsigned old = xb_add(&bar[XB_XSUB(b.x)], 1u);
;         const unsigned gen = old / nloc;
;         if (old + 1u == (gen + 1u) * nloc) {
;             __builtin_amdgcn_fence(__ATOMIC_RELEASE, "agent");
;             asm volatile("s_waitcnt vmcnt(0)" ::: "memory");
;             const unsigned og = xb_add(&bar[XB_TOP], 1u);
;             const unsigned tg = og / nx;
;             if (og + 1u == (tg + 1u) * nx) xb_add(&bar[XB_TOPGEN], 1u);
;             else XB_SPIN(xb_ld(&bar[XB_TOPGEN]) == tg, bar);
;             __builtin_amdgcn_fence(__ATOMIC_ACQUIRE, "agent");
;             xb_add(&bar[XB_XGEN(b.x)], 1u);
;             asm volatile("s_waitcnt vmcnt(0)" ::: "memory");
;         } else {
;             XB_SPIN(xb_ld(&bar[XB_XGEN(b.x)]) == gen, bar);
;             __builtin_amdgcn_fence(__ATOMIC_ACQUIRE, "agent");
;             asm volatile("s_waitcnt vmcnt(0)" ::: "memory");
;         }
;     }
;     __syncthreads();
; }
.Lsk_nowb:
.LBB0_1460:
	s_cmp_lt_i32 s56, 14
	s_cselect_b64 s[0:1], -1, 0
	s_cmp_gt_i32 s57, 13
	s_cselect_b64 s[4:5], -1, 0
	s_and_b64 s[0:1], s[0:1], s[4:5]
	s_andn2_b64 vcc, exec, s[0:1]
	s_cbranch_vccnz .LBB0_1520
	s_andn2_b64 vcc, exec, s[6:7]
	s_cbranch_vccnz .LBB0_1515
	s_getreg_b32 s3, hwreg(HW_REG_XCC_ID, 0, 4)
	s_waitcnt vmcnt(0)
	v_cmp_eq_u32_e32 vcc, 0, v178
	s_waitcnt vmcnt(0) lgkmcnt(0)
	s_barrier
	s_and_saveexec_b64 s[0:1], vcc
	s_cbranch_execz .LBB0_1514
	buffer_inv sc1
	v_mov_b32_e32 v0, 0x23ff0
	ds_read2_b32 v[0:1], v0 offset1:1
	s_and_b32 s98, s3, 15
	s_lshl_b32 s98, s98, 8
	s_add_u32 s98, s54, s98
	s_addc_u32 s99, s55, 0
	s_add_u32 s98, s98, 0x22a3400
	s_addc_u32 s99, s99, 0
	v_mov_b32_e32 v2, 0
	v_mov_b32_e32 v3, 1
	global_atomic_add v4, v2, v3, s[98:99] sc0
	s_add_u32 s100, s54, 0x22a5400
	s_addc_u32 s101, s55, 0
	s_waitcnt vmcnt(0) lgkmcnt(0)
	v_mul_u32_u24_e32 v0, 12, v0
	v_mul_u32_u24_e32 v1, 12, v1
	v_add_u32_e32 v4, 1, v4
	v_cmp_eq_u32_e32 vcc, v4, v0
	s_cbranch_vccz .Lxb_poll_s11
	buffer_wbl2 sc1
	s_waitcnt vmcnt(0)
	global_atomic_add v2, v3, s[100:101]
